# out-proj epilogue: row sum-of-squares via plain partial stores + reduction at up-proj epilogue start (no f32 atomics)
# baseline (speedup 1.0000x reference)
.LBB0_1029:
	v_lshl_or_b32 v152, s30, 8, v186
	v_lshl_add_u32 v180, s28, 8, v184
	v_bfe_u32 v246, v236, 6, 2
	s_lshl_b32 s74, s30, 2
	s_nop 0
	v_readfirstlane_b32 s75, v246
	s_add_u32 s74, s74, s75
	s_lshl_b32 s74, s74, 17
	s_add_u32 s74, s74, 0x200000
	s_add_u32 s74, s82, s74
	s_addc_u32 s75, s83, 0
	s_ashr_i32 s21, s28, 4
	v_ashrrev_i32_e32 v153, 31, v152
	v_ashrrev_i32_e32 v181, 31, v180
	s_mul_hi_i32 s23, s21, 0x9000
	s_mul_i32 s21, s21, 0x9000
	v_lshl_add_u64 v[178:179], v[152:153], 1, s[80:81]
	v_lshlrev_b64 v[128:129], 11, v[180:181]
	s_add_u32 s28, s44, s21
	v_lshl_add_u64 v[128:129], v[178:179], 0, v[128:129]
	s_addc_u32 s29, s45, s23
	v_lshlrev_b64 v[130:131], 2, v[152:153]
	global_load_dwordx4 v[154:157], v[128:129], off
	v_lshl_add_u64 v[132:133], s[28:29], 0, v[130:131]
	s_add_u32 s28, s46, s21
	s_addc_u32 s29, s47, s23
	global_load_dwordx4 v[158:161], v[132:133], off
	global_load_dwordx4 v[162:165], v[132:133], off offset:16
	global_load_dwordx4 v[166:169], v[132:133], off offset:512
	global_load_dwordx4 v[192:195], v[132:133], off offset:528
	v_lshl_add_u64 v[132:133], s[28:29], 0, v[130:131]
	global_load_dwordx4 v[196:199], v[132:133], off
	global_load_dwordx4 v[200:203], v[132:133], off offset:16
	global_load_dwordx4 v[204:207], v[132:133], off offset:512
	global_load_dwordx4 v[208:211], v[132:133], off offset:528
	v_lshl_add_u64 v[130:131], s[12:13], 0, v[130:131]
	global_load_dwordx4 v[212:215], v[130:131], off
	global_load_dwordx4 v[216:219], v[130:131], off offset:16
	global_load_dwordx4 v[220:223], v[130:131], off offset:512
	global_load_dwordx4 v[224:227], v[130:131], off offset:528
	global_load_dwordx4 v[228:231], v[128:129], off offset:256
	v_or_b32_e32 v182, 16, v180
	v_ashrrev_i32_e32 v183, 31, v182
	v_lshlrev_b64 v[128:129], 10, v[180:181]
	v_lshlrev_b64 v[130:131], 11, v[182:183]
	v_lshl_add_u64 v[128:129], v[128:129], 0, v[152:153]
	v_lshl_add_u64 v[130:131], v[178:179], 0, v[130:131]
	v_lshlrev_b64 v[232:233], 1, v[128:129]
	global_load_dwordx4 v[132:135], v[130:131], off
	s_nop 0
	global_load_dwordx4 v[128:131], v[130:131], off offset:256
	v_lshl_add_u64 v[234:235], s[94:95], 0, v[232:233]
	s_waitcnt vmcnt(0)
	v_lshlrev_b32_e32 v238, 16, v154
	v_and_b32_e32 v239, 0xffff0000, v154
	v_lshlrev_b32_e32 v242, 16, v156
	v_and_b32_e32 v243, 0xffff0000, v156
	v_lshlrev_b32_e32 v244, 16, v157
	v_and_b32_e32 v245, 0xffff0000, v157
	v_pk_add_f32 v[174:175], v[158:159], 1.0 op_sel_hi:[1,0]
	v_pk_add_f32 v[172:173], v[164:165], 1.0 op_sel_hi:[1,0]
	v_pk_add_f32 v[170:171], v[162:163], 1.0 op_sel_hi:[1,0]
	v_lshlrev_b32_e32 v240, 16, v155
	v_and_b32_e32 v241, 0xffff0000, v155
	v_pk_add_f32 v[176:177], v[160:161], 1.0 op_sel_hi:[1,0]
	v_pk_fma_f32 v[238:239], v[124:125], v[174:175], v[238:239]
	v_pk_fma_f32 v[244:245], v[122:123], v[172:173], v[244:245]
	v_pk_fma_f32 v[242:243], v[120:121], v[170:171], v[242:243]
	v_pk_add_f32 v[120:121], v[198:199], 1.0 op_sel_hi:[1,0]
	v_pk_add_f32 v[122:123], v[196:197], 1.0 op_sel_hi:[1,0]
	v_pk_add_f32 v[124:125], v[202:203], 1.0 op_sel_hi:[1,0]
	v_pk_add_f32 v[160:161], v[168:169], 1.0 op_sel_hi:[1,0]
	v_pk_add_f32 v[158:159], v[166:167], 1.0 op_sel_hi:[1,0]
	v_pk_add_f32 v[156:157], v[194:195], 1.0 op_sel_hi:[1,0]
	v_pk_add_f32 v[154:155], v[192:193], 1.0 op_sel_hi:[1,0]
	v_pk_fma_f32 v[240:241], v[126:127], v[176:177], v[240:241]
	v_pk_add_f32 v[126:127], v[200:201], 1.0 op_sel_hi:[1,0]
	v_pk_add_f32 v[196:197], v[206:207], 1.0 op_sel_hi:[1,0]
	v_cvt_pk_bf16_f32 v192, v238, v239
	v_cvt_pk_bf16_f32 v193, v240, v241
	v_cvt_pk_bf16_f32 v194, v242, v243
	v_cvt_pk_bf16_f32 v195, v244, v245
	v_pk_mul_f32 v[166:167], v[214:215], v[120:121]
	v_pk_mul_f32 v[168:169], v[212:213], v[122:123]
	v_pk_mul_f32 v[162:163], v[218:219], v[124:125]
	v_pk_add_f32 v[198:199], v[204:205], 1.0 op_sel_hi:[1,0]
	v_pk_mul_f32 v[164:165], v[216:217], v[126:127]
	v_pk_mul_f32 v[126:127], v[222:223], v[196:197]
	global_store_dwordx4 v[234:235], v[192:195], off
	v_pk_mul_f32 v[196:197], v[162:163], v[244:245]
	v_pk_mul_f32 v[124:125], v[220:221], v[198:199]
	v_pk_mul_f32 v[194:195], v[166:167], v[240:241]
	v_pk_mul_f32 v[192:193], v[168:169], v[238:239]
	v_pk_mul_f32 v[198:199], v[164:165], v[242:243]
	v_cvt_pk_bf16_f32 v192, v192, v193
	v_cvt_pk_bf16_f32 v193, v194, v195
	v_mul_f32_e32 v191, v239, v239
	v_cvt_pk_bf16_f32 v194, v198, v199
	v_cvt_pk_bf16_f32 v195, v196, v197
	v_lshl_add_u64 v[196:197], s[10:11], 0, v[232:233]
	global_store_dwordx4 v[196:197], v[192:195], off
	v_fmac_f32_e32 v191, v238, v238
	v_pk_add_f32 v[200:201], v[210:211], 1.0 op_sel_hi:[1,0]
	v_mul_f32_e32 v192, v241, v241
	v_fmac_f32_e32 v192, v240, v240
	v_add_f32_e32 v191, v191, v192
	v_mul_f32_e32 v192, v243, v243
	v_mul_f32_e32 v193, v245, v245
	v_fmac_f32_e32 v192, v242, v242
	v_fmac_f32_e32 v193, v244, v244
	v_add_f32_e32 v192, v192, v193
	v_add_f32_e32 v191, v191, v192
	v_lshlrev_b32_e32 v192, 16, v228
	v_and_b32_e32 v193, 0xffff0000, v228
	v_lshlrev_b32_e32 v194, 16, v229
	v_and_b32_e32 v195, 0xffff0000, v229
	v_lshlrev_b32_e32 v198, 16, v230
	v_and_b32_e32 v199, 0xffff0000, v230
	v_pk_mul_f32 v[120:121], v[226:227], v[200:201]
	v_lshlrev_b32_e32 v200, 16, v231
	v_and_b32_e32 v201, 0xffff0000, v231
	v_pk_fma_f32 v[118:119], v[118:119], v[160:161], v[194:195]
	v_pk_fma_f32 v[116:117], v[116:117], v[158:159], v[192:193]
	v_pk_fma_f32 v[194:195], v[112:113], v[154:155], v[198:199]
	v_cvt_pk_bf16_f32 v112, v116, v117
	v_cvt_pk_bf16_f32 v113, v118, v119
	v_pk_fma_f32 v[192:193], v[114:115], v[156:157], v[200:201]
	v_cvt_pk_bf16_f32 v114, v194, v195
	v_pk_add_f32 v[202:203], v[208:209], 1.0 op_sel_hi:[1,0]
	v_cvt_pk_bf16_f32 v115, v192, v193
	global_store_dwordx4 v[234:235], v[112:115], off offset:256
	v_pk_mul_f32 v[122:123], v[224:225], v[202:203]
	v_pk_mul_f32 v[198:199], v[126:127], v[118:119]
	v_mul_f32_e32 v112, v117, v117
	v_mul_f32_e32 v113, v119, v119
	v_fmac_f32_e32 v112, v116, v116
	v_fmac_f32_e32 v113, v118, v118
	v_add_f32_e32 v112, v112, v113
	v_mul_f32_e32 v113, v195, v195
	v_mul_f32_e32 v114, v193, v193
	v_fmac_f32_e32 v113, v194, v194
	v_fmac_f32_e32 v114, v192, v192
	v_add_f32_e32 v113, v113, v114
	v_add_f32_e32 v112, v112, v113
	v_and_b32_e32 v114, 64, v190
	v_add_f32_e32 v113, v191, v112
	v_xor_b32_e32 v112, 16, v190
	v_add_u32_e32 v191, 64, v114
	v_cmp_lt_i32_e32 vcc, v112, v191
	v_pk_mul_f32 v[114:115], v[124:125], v[116:117]
	v_pk_mul_f32 v[118:119], v[122:123], v[194:195]
	v_cndmask_b32_e32 v112, v190, v112, vcc
	v_lshlrev_b32_e32 v112, 2, v112
	ds_bpermute_b32 v200, v112, v113
	v_cvt_pk_bf16_f32 v116, v114, v115
	v_pk_mul_f32 v[192:193], v[120:121], v[192:193]
	v_cvt_pk_bf16_f32 v117, v198, v199
	v_cvt_pk_bf16_f32 v118, v118, v119
	s_waitcnt lgkmcnt(0)
	v_add_f32_e32 v114, v113, v200
	v_xor_b32_e32 v113, 32, v190
	v_cmp_lt_i32_e32 vcc, v113, v191
	v_cvt_pk_bf16_f32 v119, v192, v193
	global_store_dwordx4 v[196:197], v[116:119], off offset:256
	s_nop 0
	v_cndmask_b32_e32 v113, v190, v113, vcc
	v_lshlrev_b32_e32 v113, 2, v113
	ds_bpermute_b32 v115, v113, v114
	s_and_saveexec_b64 s[28:29], s[0:1]
	s_cbranch_execz .LBB0_1031
	v_lshl_add_u64 v[116:117], v[180:181], 2, s[74:75]
	s_waitcnt lgkmcnt(0)
	v_add_f32_e32 v114, v114, v115
	global_store_dword v[116:117], v114, off
.LBB0_1031:
	s_or_b64 exec, exec, s[28:29]
	s_waitcnt lgkmcnt(0)
	v_lshlrev_b64 v[114:115], 10, v[182:183]
	v_lshl_add_u64 v[114:115], v[114:115], 0, v[152:153]
	v_lshlrev_b32_e32 v116, 16, v132
	v_and_b32_e32 v117, 0xffff0000, v132
	v_lshlrev_b32_e32 v118, 16, v133
	v_and_b32_e32 v119, 0xffff0000, v133
	v_lshlrev_b32_e32 v132, 16, v134
	v_and_b32_e32 v133, 0xffff0000, v134
	v_lshlrev_b64 v[114:115], 1, v[114:115]
	v_lshlrev_b32_e32 v134, 16, v135
	v_and_b32_e32 v135, 0xffff0000, v135
	v_pk_fma_f32 v[110:111], v[110:111], v[176:177], v[118:119]
	v_pk_fma_f32 v[108:109], v[108:109], v[174:175], v[116:117]
	v_pk_fma_f32 v[118:119], v[104:105], v[170:171], v[132:133]
	v_cvt_pk_bf16_f32 v104, v108, v109
	v_cvt_pk_bf16_f32 v105, v110, v111
	v_lshl_add_u64 v[132:133], s[94:95], 0, v[114:115]
	v_pk_fma_f32 v[116:117], v[106:107], v[172:173], v[134:135]
	v_cvt_pk_bf16_f32 v106, v118, v119
	v_lshl_add_u64 v[114:115], s[10:11], 0, v[114:115]
	v_cvt_pk_bf16_f32 v107, v116, v117
	global_store_dwordx4 v[132:133], v[104:107], off
	v_pk_mul_f32 v[134:135], v[162:163], v[116:117]
	v_pk_mul_f32 v[192:193], v[164:165], v[118:119]
	v_pk_mul_f32 v[104:105], v[168:169], v[108:109]
	v_pk_mul_f32 v[106:107], v[166:167], v[110:111]
	v_cvt_pk_bf16_f32 v104, v104, v105
	s_nop 0
	v_cvt_pk_bf16_f32 v105, v106, v107
	v_cvt_pk_bf16_f32 v106, v192, v193
	v_cvt_pk_bf16_f32 v107, v134, v135
	global_store_dwordx4 v[114:115], v[104:107], off
	s_nop 1
	v_mul_f32_e32 v104, v109, v109
	v_mul_f32_e32 v105, v111, v111
	v_fmac_f32_e32 v104, v108, v108
	v_fmac_f32_e32 v105, v110, v110
	v_add_f32_e32 v104, v104, v105
	v_mul_f32_e32 v105, v119, v119
	v_mul_f32_e32 v106, v117, v117
	v_fmac_f32_e32 v105, v118, v118
	v_fmac_f32_e32 v106, v116, v116
	v_add_f32_e32 v105, v105, v106
	v_add_f32_e32 v116, v104, v105
	v_lshlrev_b32_e32 v104, 16, v128
	v_and_b32_e32 v105, 0xffff0000, v128
	v_lshlrev_b32_e32 v106, 16, v129
	v_and_b32_e32 v107, 0xffff0000, v129
	v_lshlrev_b32_e32 v108, 16, v130
	v_and_b32_e32 v109, 0xffff0000, v130
	v_lshlrev_b32_e32 v110, 16, v131
	v_and_b32_e32 v111, 0xffff0000, v131
	v_pk_fma_f32 v[102:103], v[102:103], v[160:161], v[106:107]
	v_pk_fma_f32 v[100:101], v[100:101], v[158:159], v[104:105]
	v_pk_fma_f32 v[106:107], v[96:97], v[154:155], v[108:109]
	v_cvt_pk_bf16_f32 v96, v100, v101
	v_cvt_pk_bf16_f32 v97, v102, v103
	v_pk_fma_f32 v[104:105], v[98:99], v[156:157], v[110:111]
	v_cvt_pk_bf16_f32 v98, v106, v107
	v_pk_mul_f32 v[108:109], v[126:127], v[102:103]
	v_cvt_pk_bf16_f32 v99, v104, v105
	global_store_dwordx4 v[132:133], v[96:99], off offset:256
	s_nop 1
	v_mul_f32_e32 v96, v101, v101
	v_mul_f32_e32 v97, v103, v103
	v_fmac_f32_e32 v96, v100, v100
	v_fmac_f32_e32 v97, v102, v102
	v_add_f32_e32 v96, v96, v97
	v_mul_f32_e32 v97, v107, v107
	v_mul_f32_e32 v98, v105, v105
	v_fmac_f32_e32 v97, v106, v106
	v_fmac_f32_e32 v98, v104, v104
	v_add_f32_e32 v97, v97, v98
	v_add_f32_e32 v96, v96, v97
	v_add_f32_e32 v99, v116, v96
	ds_bpermute_b32 v110, v112, v99
	v_pk_mul_f32 v[96:97], v[124:125], v[100:101]
	v_pk_mul_f32 v[100:101], v[122:123], v[106:107]
	v_cvt_pk_bf16_f32 v98, v96, v97
	v_pk_mul_f32 v[102:103], v[120:121], v[104:105]
	s_waitcnt lgkmcnt(0)
	v_add_f32_e32 v96, v99, v110
	ds_bpermute_b32 v97, v113, v96
	v_cvt_pk_bf16_f32 v99, v108, v109
	v_cvt_pk_bf16_f32 v100, v100, v101
	v_cvt_pk_bf16_f32 v101, v102, v103
	global_store_dwordx4 v[114:115], v[98:101], off offset:256
	s_and_saveexec_b64 s[28:29], s[0:1]
	s_cbranch_execz .LBB0_1033
	v_lshl_add_u64 v[98:99], v[182:183], 2, s[74:75]
	s_waitcnt lgkmcnt(0)
	v_add_f32_e32 v96, v96, v97
	global_store_dword v[98:99], v96, off
.LBB0_1033:
	s_or_b64 exec, exec, s[28:29]
	v_or_b32_e32 v106, 32, v180
	v_ashrrev_i32_e32 v107, 31, v106
	s_waitcnt lgkmcnt(0)
	v_lshlrev_b64 v[96:97], 11, v[106:107]
	v_lshl_add_u64 v[96:97], v[178:179], 0, v[96:97]
	global_load_dwordx4 v[108:111], v[96:97], off
	global_load_dwordx4 v[114:117], v[96:97], off offset:256
	v_or_b32_e32 v104, 48, v180
	v_ashrrev_i32_e32 v105, 31, v104
	v_lshlrev_b64 v[96:97], 11, v[104:105]
	v_lshlrev_b64 v[98:99], 10, v[106:107]
	v_lshl_add_u64 v[96:97], v[178:179], 0, v[96:97]
	v_lshl_add_u64 v[118:119], v[98:99], 0, v[152:153]
	global_load_dwordx4 v[100:103], v[96:97], off
	s_nop 0
	global_load_dwordx4 v[96:99], v[96:97], off offset:256
	v_lshlrev_b64 v[118:119], 1, v[118:119]
	v_lshl_add_u64 v[128:129], s[94:95], 0, v[118:119]
	v_lshl_add_u64 v[118:119], s[10:11], 0, v[118:119]
	s_waitcnt vmcnt(3)
	v_lshlrev_b32_e32 v130, 16, v108
	v_and_b32_e32 v131, 0xffff0000, v108
	v_lshlrev_b32_e32 v108, 16, v109
	v_and_b32_e32 v109, 0xffff0000, v109
	v_lshlrev_b32_e32 v132, 16, v110
	v_and_b32_e32 v133, 0xffff0000, v110
	v_lshlrev_b32_e32 v110, 16, v111
	v_and_b32_e32 v111, 0xffff0000, v111
	s_waitcnt vmcnt(2)
	v_lshlrev_b32_e32 v134, 16, v114
	v_and_b32_e32 v135, 0xffff0000, v114
	v_lshlrev_b32_e32 v114, 16, v115
	v_and_b32_e32 v115, 0xffff0000, v115
	v_lshlrev_b32_e32 v182, 16, v116
	v_and_b32_e32 v183, 0xffff0000, v116
	v_lshlrev_b32_e32 v116, 16, v117
	v_and_b32_e32 v117, 0xffff0000, v117
	v_pk_fma_f32 v[94:95], v[94:95], v[176:177], v[108:109]
	v_pk_fma_f32 v[92:93], v[92:93], v[174:175], v[130:131]
	v_pk_fma_f32 v[90:91], v[90:91], v[172:173], v[110:111]
	v_pk_fma_f32 v[88:89], v[88:89], v[170:171], v[132:133]
	v_pk_fma_f32 v[86:87], v[86:87], v[160:161], v[114:115]
	v_pk_fma_f32 v[84:85], v[84:85], v[158:159], v[134:135]
	v_pk_fma_f32 v[108:109], v[82:83], v[156:157], v[116:117]
	v_pk_fma_f32 v[110:111], v[80:81], v[154:155], v[182:183]
	v_cvt_pk_bf16_f32 v80, v92, v93
	v_cvt_pk_bf16_f32 v81, v94, v95
	v_cvt_pk_bf16_f32 v82, v88, v89
	v_cvt_pk_bf16_f32 v83, v90, v91
	v_pk_mul_f32 v[114:115], v[166:167], v[94:95]
	v_pk_mul_f32 v[116:117], v[168:169], v[92:93]
	v_pk_mul_f32 v[130:131], v[162:163], v[90:91]
	v_pk_mul_f32 v[132:133], v[164:165], v[88:89]
	v_mul_f32_e32 v93, v93, v93
	v_mul_f32_e32 v95, v95, v95
	v_mul_f32_e32 v89, v89, v89
	v_mul_f32_e32 v91, v91, v91
	v_mul_f32_e32 v181, v85, v85
	v_mul_f32_e32 v182, v87, v87
	v_mul_f32_e32 v183, v111, v111
	v_mul_f32_e32 v191, v109, v109
	global_store_dwordx4 v[128:129], v[80:83], off
	v_fmac_f32_e32 v93, v92, v92
	v_fmac_f32_e32 v95, v94, v94
	v_cvt_pk_bf16_f32 v80, v116, v117
	v_cvt_pk_bf16_f32 v81, v114, v115
	v_fmac_f32_e32 v89, v88, v88
	v_fmac_f32_e32 v91, v90, v90
	v_fmac_f32_e32 v181, v84, v84
	v_fmac_f32_e32 v182, v86, v86
	v_fmac_f32_e32 v183, v110, v110
	v_fmac_f32_e32 v191, v108, v108
	v_pk_mul_f32 v[134:135], v[126:127], v[86:87]
	v_cvt_pk_bf16_f32 v82, v132, v133
	v_cvt_pk_bf16_f32 v83, v130, v131
	global_store_dwordx4 v[118:119], v[80:83], off
	v_add_f32_e32 v88, v93, v95
	v_add_f32_e32 v89, v89, v91
	v_cvt_pk_bf16_f32 v80, v84, v85
	v_cvt_pk_bf16_f32 v81, v86, v87
	v_add_f32_e32 v86, v181, v182
	v_add_f32_e32 v87, v183, v191
	v_cvt_pk_bf16_f32 v82, v110, v111
	v_cvt_pk_bf16_f32 v83, v108, v109
	v_add_f32_e32 v88, v88, v89
	global_store_dwordx4 v[128:129], v[80:83], off offset:256
	s_nop 1
	v_add_f32_e32 v80, v86, v87
	v_add_f32_e32 v83, v88, v80
	ds_bpermute_b32 v88, v112, v83
	v_pk_mul_f32 v[80:81], v[124:125], v[84:85]
	v_pk_mul_f32 v[84:85], v[122:123], v[110:111]
	v_cvt_pk_bf16_f32 v82, v80, v81
	v_pk_mul_f32 v[86:87], v[120:121], v[108:109]
	s_waitcnt lgkmcnt(0)
	v_add_f32_e32 v80, v83, v88
	ds_bpermute_b32 v81, v113, v80
	v_cvt_pk_bf16_f32 v83, v134, v135
	v_cvt_pk_bf16_f32 v84, v84, v85
	v_cvt_pk_bf16_f32 v85, v86, v87
	global_store_dwordx4 v[118:119], v[82:85], off offset:256
	s_and_saveexec_b64 s[28:29], s[0:1]
	s_cbranch_execz .LBB0_1035
	v_lshl_add_u64 v[82:83], v[106:107], 2, s[74:75]
	s_waitcnt lgkmcnt(0)
	v_add_f32_e32 v80, v80, v81
	global_store_dword v[82:83], v80, off
.LBB0_1035:
	s_or_b64 exec, exec, s[28:29]
	s_waitcnt lgkmcnt(0)
	v_lshlrev_b64 v[80:81], 10, v[104:105]
	v_lshl_add_u64 v[80:81], v[80:81], 0, v[152:153]
	s_waitcnt vmcnt(5)
	v_lshlrev_b32_e32 v82, 16, v100
	v_and_b32_e32 v83, 0xffff0000, v100
	v_lshlrev_b32_e32 v84, 16, v101
	v_and_b32_e32 v85, 0xffff0000, v101
	v_lshlrev_b32_e32 v86, 16, v102
	v_and_b32_e32 v87, 0xffff0000, v102
	v_lshlrev_b64 v[80:81], 1, v[80:81]
	v_lshlrev_b32_e32 v88, 16, v103
	v_and_b32_e32 v89, 0xffff0000, v103
	v_pk_fma_f32 v[78:79], v[78:79], v[176:177], v[84:85]
	v_pk_fma_f32 v[76:77], v[76:77], v[174:175], v[82:83]
	v_pk_fma_f32 v[84:85], v[72:73], v[170:171], v[86:87]
	v_cvt_pk_bf16_f32 v72, v76, v77
	v_cvt_pk_bf16_f32 v73, v78, v79
	v_lshl_add_u64 v[86:87], s[94:95], 0, v[80:81]
	v_pk_fma_f32 v[82:83], v[74:75], v[172:173], v[88:89]
	v_cvt_pk_bf16_f32 v74, v84, v85
	v_lshl_add_u64 v[80:81], s[10:11], 0, v[80:81]
	v_cvt_pk_bf16_f32 v75, v82, v83
	global_store_dwordx4 v[86:87], v[72:75], off
	v_pk_mul_f32 v[88:89], v[162:163], v[82:83]
	v_pk_mul_f32 v[90:91], v[164:165], v[84:85]
	v_pk_mul_f32 v[72:73], v[168:169], v[76:77]
	v_pk_mul_f32 v[74:75], v[166:167], v[78:79]
	v_cvt_pk_bf16_f32 v72, v72, v73
	s_nop 0
	v_cvt_pk_bf16_f32 v73, v74, v75
	v_cvt_pk_bf16_f32 v74, v90, v91
	v_cvt_pk_bf16_f32 v75, v88, v89
	global_store_dwordx4 v[80:81], v[72:75], off
	s_nop 1
	v_mul_f32_e32 v72, v77, v77
	v_mul_f32_e32 v73, v79, v79
	v_fmac_f32_e32 v72, v76, v76
	v_fmac_f32_e32 v73, v78, v78
	v_add_f32_e32 v72, v72, v73
	v_mul_f32_e32 v73, v85, v85
	v_mul_f32_e32 v74, v83, v83
	v_fmac_f32_e32 v73, v84, v84
	v_fmac_f32_e32 v74, v82, v82
	v_add_f32_e32 v73, v73, v74
	v_add_f32_e32 v82, v72, v73
	s_waitcnt vmcnt(6)
	v_lshlrev_b32_e32 v72, 16, v96
	v_and_b32_e32 v73, 0xffff0000, v96
	v_lshlrev_b32_e32 v74, 16, v97
	v_and_b32_e32 v75, 0xffff0000, v97
	v_lshlrev_b32_e32 v76, 16, v98
	v_and_b32_e32 v77, 0xffff0000, v98
	v_lshlrev_b32_e32 v78, 16, v99
	v_and_b32_e32 v79, 0xffff0000, v99
	v_pk_fma_f32 v[70:71], v[70:71], v[160:161], v[74:75]
	v_pk_fma_f32 v[68:69], v[68:69], v[158:159], v[72:73]
	v_pk_fma_f32 v[74:75], v[64:65], v[154:155], v[76:77]
	v_cvt_pk_bf16_f32 v64, v68, v69
	v_cvt_pk_bf16_f32 v65, v70, v71
	v_pk_fma_f32 v[72:73], v[66:67], v[156:157], v[78:79]
	v_cvt_pk_bf16_f32 v66, v74, v75
	v_pk_mul_f32 v[76:77], v[126:127], v[70:71]
	v_cvt_pk_bf16_f32 v67, v72, v73
	global_store_dwordx4 v[86:87], v[64:67], off offset:256
	s_nop 1
	v_mul_f32_e32 v64, v69, v69
	v_mul_f32_e32 v65, v71, v71
	v_fmac_f32_e32 v64, v68, v68
	v_fmac_f32_e32 v65, v70, v70
	v_add_f32_e32 v64, v64, v65
	v_mul_f32_e32 v65, v75, v75
	v_mul_f32_e32 v66, v73, v73
	v_fmac_f32_e32 v65, v74, v74
	v_fmac_f32_e32 v66, v72, v72
	v_add_f32_e32 v65, v65, v66
	v_add_f32_e32 v64, v64, v65
	v_add_f32_e32 v67, v82, v64
	ds_bpermute_b32 v78, v112, v67
	v_pk_mul_f32 v[64:65], v[124:125], v[68:69]
	v_pk_mul_f32 v[68:69], v[122:123], v[74:75]
	v_cvt_pk_bf16_f32 v66, v64, v65
	v_pk_mul_f32 v[70:71], v[120:121], v[72:73]
	s_waitcnt lgkmcnt(0)
	v_add_f32_e32 v64, v67, v78
	ds_bpermute_b32 v65, v113, v64
	v_cvt_pk_bf16_f32 v67, v76, v77
	v_cvt_pk_bf16_f32 v68, v68, v69
	v_cvt_pk_bf16_f32 v69, v70, v71
	global_store_dwordx4 v[80:81], v[66:69], off offset:256
	s_and_saveexec_b64 s[28:29], s[0:1]
	s_cbranch_execz .LBB0_1037
	v_lshl_add_u64 v[66:67], v[104:105], 2, s[74:75]
	s_waitcnt lgkmcnt(0)
	v_add_f32_e32 v64, v64, v65
	global_store_dword v[66:67], v64, off
.LBB0_1037:
	s_or_b64 exec, exec, s[28:29]
	v_add_u32_e32 v74, 0x80, v180
	v_ashrrev_i32_e32 v75, 31, v74
	s_waitcnt lgkmcnt(0)
	v_lshlrev_b64 v[64:65], 11, v[74:75]
	v_lshl_add_u64 v[64:65], v[178:179], 0, v[64:65]
	global_load_dwordx4 v[76:79], v[64:65], off
	global_load_dwordx4 v[80:83], v[64:65], off offset:256
	v_add_u32_e32 v72, 0x90, v180
	v_ashrrev_i32_e32 v73, 31, v72
	v_lshlrev_b64 v[64:65], 11, v[72:73]
	v_lshlrev_b64 v[66:67], 10, v[74:75]
	v_lshl_add_u64 v[64:65], v[178:179], 0, v[64:65]
	v_lshl_add_u64 v[84:85], v[66:67], 0, v[152:153]
	global_load_dwordx4 v[68:71], v[64:65], off
	s_nop 0
	global_load_dwordx4 v[64:67], v[64:65], off offset:256
	v_lshlrev_b64 v[84:85], 1, v[84:85]
	v_lshl_add_u64 v[86:87], s[94:95], 0, v[84:85]
	v_lshl_add_u64 v[84:85], s[10:11], 0, v[84:85]
	s_waitcnt vmcnt(3)
	v_lshlrev_b32_e32 v88, 16, v76
	v_and_b32_e32 v89, 0xffff0000, v76
	v_lshlrev_b32_e32 v76, 16, v77
	v_and_b32_e32 v77, 0xffff0000, v77
	v_lshlrev_b32_e32 v90, 16, v78
	v_and_b32_e32 v91, 0xffff0000, v78
	v_lshlrev_b32_e32 v78, 16, v79
	v_and_b32_e32 v79, 0xffff0000, v79
	s_waitcnt vmcnt(2)
	v_lshlrev_b32_e32 v92, 16, v80
	v_and_b32_e32 v93, 0xffff0000, v80
	v_lshlrev_b32_e32 v80, 16, v81
	v_and_b32_e32 v81, 0xffff0000, v81
	v_lshlrev_b32_e32 v94, 16, v82
	v_and_b32_e32 v95, 0xffff0000, v82
	v_lshlrev_b32_e32 v82, 16, v83
	v_and_b32_e32 v83, 0xffff0000, v83
	v_pk_fma_f32 v[62:63], v[62:63], v[176:177], v[76:77]
	v_pk_fma_f32 v[60:61], v[60:61], v[174:175], v[88:89]
	v_pk_fma_f32 v[58:59], v[58:59], v[172:173], v[78:79]
	v_pk_fma_f32 v[56:57], v[56:57], v[170:171], v[90:91]
	v_pk_fma_f32 v[54:55], v[54:55], v[160:161], v[80:81]
	v_pk_fma_f32 v[52:53], v[52:53], v[158:159], v[92:93]
	v_pk_fma_f32 v[76:77], v[50:51], v[156:157], v[82:83]
	v_pk_fma_f32 v[78:79], v[48:49], v[154:155], v[94:95]
	v_cvt_pk_bf16_f32 v48, v60, v61
	v_cvt_pk_bf16_f32 v49, v62, v63
	v_cvt_pk_bf16_f32 v50, v56, v57
	v_cvt_pk_bf16_f32 v51, v58, v59
	v_pk_mul_f32 v[80:81], v[166:167], v[62:63]
	v_pk_mul_f32 v[82:83], v[168:169], v[60:61]
	v_pk_mul_f32 v[88:89], v[162:163], v[58:59]
	v_pk_mul_f32 v[90:91], v[164:165], v[56:57]
	v_mul_f32_e32 v61, v61, v61
	v_mul_f32_e32 v63, v63, v63
	v_mul_f32_e32 v57, v57, v57
	v_mul_f32_e32 v59, v59, v59
	v_mul_f32_e32 v94, v53, v53
	v_mul_f32_e32 v95, v55, v55
	v_mul_f32_e32 v96, v79, v79
	v_mul_f32_e32 v97, v77, v77
	global_store_dwordx4 v[86:87], v[48:51], off
	v_fmac_f32_e32 v61, v60, v60
	v_fmac_f32_e32 v63, v62, v62
	v_cvt_pk_bf16_f32 v48, v82, v83
	v_cvt_pk_bf16_f32 v49, v80, v81
	v_fmac_f32_e32 v57, v56, v56
	v_fmac_f32_e32 v59, v58, v58
	v_fmac_f32_e32 v94, v52, v52
	v_fmac_f32_e32 v95, v54, v54
	v_fmac_f32_e32 v96, v78, v78
	v_fmac_f32_e32 v97, v76, v76
	v_pk_mul_f32 v[92:93], v[126:127], v[54:55]
	v_cvt_pk_bf16_f32 v50, v90, v91
	v_cvt_pk_bf16_f32 v51, v88, v89
	global_store_dwordx4 v[84:85], v[48:51], off
	v_add_f32_e32 v56, v61, v63
	v_add_f32_e32 v57, v57, v59
	v_cvt_pk_bf16_f32 v48, v52, v53
	v_cvt_pk_bf16_f32 v49, v54, v55
	v_add_f32_e32 v54, v94, v95
	v_add_f32_e32 v55, v96, v97
	v_cvt_pk_bf16_f32 v50, v78, v79
	v_cvt_pk_bf16_f32 v51, v76, v77
	v_add_f32_e32 v56, v56, v57
	global_store_dwordx4 v[86:87], v[48:51], off offset:256
	s_nop 1
	v_add_f32_e32 v48, v54, v55
	v_add_f32_e32 v51, v56, v48
	ds_bpermute_b32 v56, v112, v51
	v_pk_mul_f32 v[48:49], v[124:125], v[52:53]
	v_pk_mul_f32 v[52:53], v[122:123], v[78:79]
	v_cvt_pk_bf16_f32 v50, v48, v49
	v_pk_mul_f32 v[54:55], v[120:121], v[76:77]
	s_waitcnt lgkmcnt(0)
	v_add_f32_e32 v48, v51, v56
	ds_bpermute_b32 v49, v113, v48
	v_cvt_pk_bf16_f32 v51, v92, v93
	v_cvt_pk_bf16_f32 v52, v52, v53
	v_cvt_pk_bf16_f32 v53, v54, v55
	global_store_dwordx4 v[84:85], v[50:53], off offset:256
	s_and_saveexec_b64 s[28:29], s[0:1]
	s_cbranch_execz .LBB0_1039
	v_lshl_add_u64 v[50:51], v[74:75], 2, s[74:75]
	s_waitcnt lgkmcnt(0)
	v_add_f32_e32 v48, v48, v49
	global_store_dword v[50:51], v48, off
.LBB0_1039:
	s_or_b64 exec, exec, s[28:29]
	s_waitcnt lgkmcnt(0)
	v_lshlrev_b64 v[48:49], 10, v[72:73]
	v_lshl_add_u64 v[48:49], v[48:49], 0, v[152:153]
	s_waitcnt vmcnt(5)
	v_lshlrev_b32_e32 v50, 16, v68
	v_and_b32_e32 v51, 0xffff0000, v68
	v_lshlrev_b32_e32 v52, 16, v69
	v_and_b32_e32 v53, 0xffff0000, v69
	v_lshlrev_b32_e32 v54, 16, v70
	v_and_b32_e32 v55, 0xffff0000, v70
	v_lshlrev_b64 v[48:49], 1, v[48:49]
	v_lshlrev_b32_e32 v56, 16, v71
	v_and_b32_e32 v57, 0xffff0000, v71
	v_pk_fma_f32 v[46:47], v[46:47], v[176:177], v[52:53]
	v_pk_fma_f32 v[44:45], v[44:45], v[174:175], v[50:51]
	v_pk_fma_f32 v[52:53], v[40:41], v[170:171], v[54:55]
	v_cvt_pk_bf16_f32 v40, v44, v45
	v_cvt_pk_bf16_f32 v41, v46, v47
	v_lshl_add_u64 v[54:55], s[94:95], 0, v[48:49]
	v_pk_fma_f32 v[50:51], v[42:43], v[172:173], v[56:57]
	v_cvt_pk_bf16_f32 v42, v52, v53
	v_lshl_add_u64 v[48:49], s[10:11], 0, v[48:49]
	v_cvt_pk_bf16_f32 v43, v50, v51
	global_store_dwordx4 v[54:55], v[40:43], off
	v_pk_mul_f32 v[56:57], v[162:163], v[50:51]
	v_pk_mul_f32 v[58:59], v[164:165], v[52:53]
	v_pk_mul_f32 v[40:41], v[168:169], v[44:45]
	v_pk_mul_f32 v[42:43], v[166:167], v[46:47]
	v_cvt_pk_bf16_f32 v40, v40, v41
	s_nop 0
	v_cvt_pk_bf16_f32 v41, v42, v43
	v_cvt_pk_bf16_f32 v42, v58, v59
	v_cvt_pk_bf16_f32 v43, v56, v57
	global_store_dwordx4 v[48:49], v[40:43], off
	s_nop 1
	v_mul_f32_e32 v40, v45, v45
	v_mul_f32_e32 v41, v47, v47
	v_fmac_f32_e32 v40, v44, v44
	v_fmac_f32_e32 v41, v46, v46
	v_add_f32_e32 v40, v40, v41
	v_mul_f32_e32 v41, v53, v53
	v_mul_f32_e32 v42, v51, v51
	v_fmac_f32_e32 v41, v52, v52
	v_fmac_f32_e32 v42, v50, v50
	v_add_f32_e32 v41, v41, v42
	v_add_f32_e32 v50, v40, v41
	s_waitcnt vmcnt(6)
	v_lshlrev_b32_e32 v40, 16, v64
	v_and_b32_e32 v41, 0xffff0000, v64
	v_lshlrev_b32_e32 v42, 16, v65
	v_and_b32_e32 v43, 0xffff0000, v65
	v_lshlrev_b32_e32 v44, 16, v66
	v_and_b32_e32 v45, 0xffff0000, v66
	v_lshlrev_b32_e32 v46, 16, v67
	v_and_b32_e32 v47, 0xffff0000, v67
	v_pk_fma_f32 v[38:39], v[38:39], v[160:161], v[42:43]
	v_pk_fma_f32 v[36:37], v[36:37], v[158:159], v[40:41]
	v_pk_fma_f32 v[42:43], v[32:33], v[154:155], v[44:45]
	v_cvt_pk_bf16_f32 v32, v36, v37
	v_cvt_pk_bf16_f32 v33, v38, v39
	v_pk_fma_f32 v[40:41], v[34:35], v[156:157], v[46:47]
	v_cvt_pk_bf16_f32 v34, v42, v43
	v_pk_mul_f32 v[44:45], v[126:127], v[38:39]
	v_cvt_pk_bf16_f32 v35, v40, v41
	global_store_dwordx4 v[54:55], v[32:35], off offset:256
	s_nop 1
	v_mul_f32_e32 v32, v37, v37
	v_mul_f32_e32 v33, v39, v39
	v_fmac_f32_e32 v32, v36, v36
	v_fmac_f32_e32 v33, v38, v38
	v_add_f32_e32 v32, v32, v33
	v_mul_f32_e32 v33, v43, v43
	v_mul_f32_e32 v34, v41, v41
	v_fmac_f32_e32 v33, v42, v42
	v_fmac_f32_e32 v34, v40, v40
	v_add_f32_e32 v33, v33, v34
	v_add_f32_e32 v32, v32, v33
	v_add_f32_e32 v35, v50, v32
	ds_bpermute_b32 v46, v112, v35
	v_pk_mul_f32 v[32:33], v[124:125], v[36:37]
	v_pk_mul_f32 v[36:37], v[122:123], v[42:43]
	v_cvt_pk_bf16_f32 v34, v32, v33
	v_pk_mul_f32 v[38:39], v[120:121], v[40:41]
	s_waitcnt lgkmcnt(0)
	v_add_f32_e32 v32, v35, v46
	ds_bpermute_b32 v33, v113, v32
	v_cvt_pk_bf16_f32 v35, v44, v45
	v_cvt_pk_bf16_f32 v36, v36, v37
	v_cvt_pk_bf16_f32 v37, v38, v39
	global_store_dwordx4 v[48:49], v[34:37], off offset:256
	s_and_saveexec_b64 s[28:29], s[0:1]
	s_cbranch_execz .LBB0_1041
	v_lshl_add_u64 v[34:35], v[72:73], 2, s[74:75]
	s_waitcnt lgkmcnt(0)
	v_add_f32_e32 v32, v32, v33
	global_store_dword v[34:35], v32, off
.LBB0_1041:
	s_or_b64 exec, exec, s[28:29]
	v_add_u32_e32 v42, 0xa0, v180
	v_ashrrev_i32_e32 v43, 31, v42
	s_waitcnt lgkmcnt(0)
	v_lshlrev_b64 v[32:33], 11, v[42:43]
	v_lshl_add_u64 v[32:33], v[178:179], 0, v[32:33]
	global_load_dwordx4 v[44:47], v[32:33], off
	global_load_dwordx4 v[48:51], v[32:33], off offset:256
	v_add_u32_e32 v40, 0xb0, v180
	v_ashrrev_i32_e32 v41, 31, v40
	v_lshlrev_b64 v[32:33], 11, v[40:41]
	v_lshlrev_b64 v[34:35], 10, v[42:43]
	v_lshl_add_u64 v[32:33], v[178:179], 0, v[32:33]
	v_lshl_add_u64 v[52:53], v[34:35], 0, v[152:153]
	global_load_dwordx4 v[36:39], v[32:33], off
	s_nop 0
	global_load_dwordx4 v[32:35], v[32:33], off offset:256
	v_lshlrev_b64 v[52:53], 1, v[52:53]
	v_lshl_add_u64 v[54:55], s[94:95], 0, v[52:53]
	v_lshl_add_u64 v[52:53], s[10:11], 0, v[52:53]
	s_waitcnt vmcnt(3)
	v_lshlrev_b32_e32 v56, 16, v44
	v_and_b32_e32 v57, 0xffff0000, v44
	v_lshlrev_b32_e32 v44, 16, v45
	v_and_b32_e32 v45, 0xffff0000, v45
	v_lshlrev_b32_e32 v58, 16, v46
	v_and_b32_e32 v59, 0xffff0000, v46
	v_lshlrev_b32_e32 v46, 16, v47
	v_and_b32_e32 v47, 0xffff0000, v47
	s_waitcnt vmcnt(2)
	v_lshlrev_b32_e32 v60, 16, v48
	v_and_b32_e32 v61, 0xffff0000, v48
	v_lshlrev_b32_e32 v48, 16, v49
	v_and_b32_e32 v49, 0xffff0000, v49
	v_lshlrev_b32_e32 v62, 16, v50
	v_and_b32_e32 v63, 0xffff0000, v50
	v_lshlrev_b32_e32 v50, 16, v51
	v_and_b32_e32 v51, 0xffff0000, v51
	v_pk_fma_f32 v[30:31], v[30:31], v[176:177], v[44:45]
	v_pk_fma_f32 v[28:29], v[28:29], v[174:175], v[56:57]
	v_pk_fma_f32 v[26:27], v[26:27], v[172:173], v[46:47]
	v_pk_fma_f32 v[24:25], v[24:25], v[170:171], v[58:59]
	v_pk_fma_f32 v[22:23], v[22:23], v[160:161], v[48:49]
	v_pk_fma_f32 v[20:21], v[20:21], v[158:159], v[60:61]
	v_pk_fma_f32 v[44:45], v[18:19], v[156:157], v[50:51]
	v_pk_fma_f32 v[46:47], v[16:17], v[154:155], v[62:63]
	v_cvt_pk_bf16_f32 v16, v28, v29
	v_cvt_pk_bf16_f32 v17, v30, v31
	v_cvt_pk_bf16_f32 v18, v24, v25
	v_cvt_pk_bf16_f32 v19, v26, v27
	v_pk_mul_f32 v[48:49], v[166:167], v[30:31]
	v_pk_mul_f32 v[50:51], v[168:169], v[28:29]
	v_pk_mul_f32 v[56:57], v[162:163], v[26:27]
	v_pk_mul_f32 v[58:59], v[164:165], v[24:25]
	v_mul_f32_e32 v29, v29, v29
	v_mul_f32_e32 v31, v31, v31
	v_mul_f32_e32 v25, v25, v25
	v_mul_f32_e32 v27, v27, v27
	v_mul_f32_e32 v62, v21, v21
	v_mul_f32_e32 v63, v23, v23
	v_mul_f32_e32 v64, v47, v47
	v_mul_f32_e32 v65, v45, v45
	global_store_dwordx4 v[54:55], v[16:19], off
	v_fmac_f32_e32 v29, v28, v28
	v_fmac_f32_e32 v31, v30, v30
	v_cvt_pk_bf16_f32 v16, v50, v51
	v_cvt_pk_bf16_f32 v17, v48, v49
	v_fmac_f32_e32 v25, v24, v24
	v_fmac_f32_e32 v27, v26, v26
	v_fmac_f32_e32 v62, v20, v20
	v_fmac_f32_e32 v63, v22, v22
	v_fmac_f32_e32 v64, v46, v46
	v_fmac_f32_e32 v65, v44, v44
	v_pk_mul_f32 v[60:61], v[126:127], v[22:23]
	v_cvt_pk_bf16_f32 v18, v58, v59
	v_cvt_pk_bf16_f32 v19, v56, v57
	global_store_dwordx4 v[52:53], v[16:19], off
	v_add_f32_e32 v24, v29, v31
	v_add_f32_e32 v25, v25, v27
	v_cvt_pk_bf16_f32 v16, v20, v21
	v_cvt_pk_bf16_f32 v17, v22, v23
	v_add_f32_e32 v22, v62, v63
	v_add_f32_e32 v23, v64, v65
	v_cvt_pk_bf16_f32 v18, v46, v47
	v_cvt_pk_bf16_f32 v19, v44, v45
	v_add_f32_e32 v24, v24, v25
	global_store_dwordx4 v[54:55], v[16:19], off offset:256
	s_nop 1
	v_add_f32_e32 v16, v22, v23
	v_add_f32_e32 v19, v24, v16
	ds_bpermute_b32 v24, v112, v19
	v_pk_mul_f32 v[16:17], v[124:125], v[20:21]
	v_pk_mul_f32 v[20:21], v[122:123], v[46:47]
	v_cvt_pk_bf16_f32 v18, v16, v17
	v_pk_mul_f32 v[22:23], v[120:121], v[44:45]
	s_waitcnt lgkmcnt(0)
	v_add_f32_e32 v16, v19, v24
	ds_bpermute_b32 v17, v113, v16
	v_cvt_pk_bf16_f32 v19, v60, v61
	v_cvt_pk_bf16_f32 v20, v20, v21
	v_cvt_pk_bf16_f32 v21, v22, v23
	global_store_dwordx4 v[52:53], v[18:21], off offset:256
	s_and_saveexec_b64 s[28:29], s[0:1]
	s_cbranch_execz .LBB0_1043
	v_lshl_add_u64 v[18:19], v[42:43], 2, s[74:75]
	s_waitcnt lgkmcnt(0)
	v_add_f32_e32 v16, v16, v17
	global_store_dword v[18:19], v16, off
.LBB0_1043:
	s_or_b64 exec, exec, s[28:29]
	s_waitcnt lgkmcnt(0)
	v_lshlrev_b64 v[16:17], 10, v[40:41]
	v_lshl_add_u64 v[16:17], v[16:17], 0, v[152:153]
	s_waitcnt vmcnt(5)
	v_lshlrev_b32_e32 v18, 16, v36
	v_and_b32_e32 v19, 0xffff0000, v36
	v_lshlrev_b32_e32 v20, 16, v37
	v_and_b32_e32 v21, 0xffff0000, v37
	v_lshlrev_b32_e32 v22, 16, v38
	v_and_b32_e32 v23, 0xffff0000, v38
	v_lshlrev_b64 v[16:17], 1, v[16:17]
	v_lshlrev_b32_e32 v24, 16, v39
	v_and_b32_e32 v25, 0xffff0000, v39
	v_pk_fma_f32 v[14:15], v[14:15], v[176:177], v[20:21]
	v_pk_fma_f32 v[12:13], v[12:13], v[174:175], v[18:19]
	v_pk_fma_f32 v[20:21], v[8:9], v[170:171], v[22:23]
	v_cvt_pk_bf16_f32 v8, v12, v13
	v_cvt_pk_bf16_f32 v9, v14, v15
	v_lshl_add_u64 v[22:23], s[94:95], 0, v[16:17]
	v_pk_fma_f32 v[18:19], v[10:11], v[172:173], v[24:25]
	v_cvt_pk_bf16_f32 v10, v20, v21
	v_lshl_add_u64 v[16:17], s[10:11], 0, v[16:17]
	v_cvt_pk_bf16_f32 v11, v18, v19
	global_store_dwordx4 v[22:23], v[8:11], off
	v_pk_mul_f32 v[24:25], v[162:163], v[18:19]
	v_pk_mul_f32 v[26:27], v[164:165], v[20:21]
	v_pk_mul_f32 v[8:9], v[168:169], v[12:13]
	v_pk_mul_f32 v[10:11], v[166:167], v[14:15]
	v_cvt_pk_bf16_f32 v8, v8, v9
	s_nop 0
	v_cvt_pk_bf16_f32 v9, v10, v11
	v_cvt_pk_bf16_f32 v10, v26, v27
	v_cvt_pk_bf16_f32 v11, v24, v25
	global_store_dwordx4 v[16:17], v[8:11], off
	s_nop 1
	v_mul_f32_e32 v8, v13, v13
	v_mul_f32_e32 v9, v15, v15
	v_fmac_f32_e32 v8, v12, v12
	v_fmac_f32_e32 v9, v14, v14
	v_add_f32_e32 v8, v8, v9
	v_mul_f32_e32 v9, v21, v21
	v_mul_f32_e32 v10, v19, v19
	v_fmac_f32_e32 v9, v20, v20
	v_fmac_f32_e32 v10, v18, v18
	v_add_f32_e32 v9, v9, v10
	v_add_f32_e32 v18, v8, v9
	s_waitcnt vmcnt(6)
	v_lshlrev_b32_e32 v8, 16, v32
	v_and_b32_e32 v9, 0xffff0000, v32
	v_lshlrev_b32_e32 v10, 16, v33
	v_and_b32_e32 v11, 0xffff0000, v33
	v_lshlrev_b32_e32 v12, 16, v34
	v_and_b32_e32 v13, 0xffff0000, v34
	v_lshlrev_b32_e32 v14, 16, v35
	v_and_b32_e32 v15, 0xffff0000, v35
	v_pk_fma_f32 v[6:7], v[6:7], v[160:161], v[10:11]
	v_pk_fma_f32 v[4:5], v[4:5], v[158:159], v[8:9]
	v_pk_fma_f32 v[10:11], v[0:1], v[154:155], v[12:13]
	v_cvt_pk_bf16_f32 v0, v4, v5
	v_cvt_pk_bf16_f32 v1, v6, v7
	v_pk_fma_f32 v[8:9], v[2:3], v[156:157], v[14:15]
	v_cvt_pk_bf16_f32 v2, v10, v11
	v_pk_mul_f32 v[12:13], v[126:127], v[6:7]
	v_cvt_pk_bf16_f32 v3, v8, v9
	global_store_dwordx4 v[22:23], v[0:3], off offset:256
	s_nop 1
	v_mul_f32_e32 v0, v5, v5
	v_mul_f32_e32 v1, v7, v7
	v_fmac_f32_e32 v0, v4, v4
	v_fmac_f32_e32 v1, v6, v6
	v_add_f32_e32 v0, v0, v1
	v_mul_f32_e32 v1, v11, v11
	v_mul_f32_e32 v2, v9, v9
	v_fmac_f32_e32 v1, v10, v10
	v_fmac_f32_e32 v2, v8, v8
	v_add_f32_e32 v1, v1, v2
	v_add_f32_e32 v0, v0, v1
	v_add_f32_e32 v3, v18, v0
	ds_bpermute_b32 v14, v112, v3
	v_pk_mul_f32 v[0:1], v[124:125], v[4:5]
	v_pk_mul_f32 v[4:5], v[122:123], v[10:11]
	v_cvt_pk_bf16_f32 v2, v0, v1
	v_pk_mul_f32 v[6:7], v[120:121], v[8:9]
	s_waitcnt lgkmcnt(0)
	v_add_f32_e32 v0, v3, v14
	ds_bpermute_b32 v1, v113, v0
	v_cvt_pk_bf16_f32 v3, v12, v13
	v_cvt_pk_bf16_f32 v4, v4, v5
	v_cvt_pk_bf16_f32 v5, v6, v7
	global_store_dwordx4 v[16:17], v[2:5], off offset:256
	s_and_saveexec_b64 s[28:29], s[0:1]
	s_cbranch_execz .LBB0_1045
	v_lshl_add_u64 v[2:3], v[40:41], 2, s[74:75]
	s_waitcnt lgkmcnt(0)
	v_add_f32_e32 v0, v0, v1
	global_store_dword v[2:3], v0, off

.LBB0_1103:
	s_cmp_lt_i32 s84, 12
	s_cselect_b64 s[0:1], -1, 0
	s_cmp_gt_i32 s85, 11
	s_cselect_b64 s[2:3], -1, 0
	s_and_b64 s[4:5], s[0:1], s[2:3]
	s_andn2_b64 vcc, exec, s[4:5]
	s_cbranch_vccnz .LBB0_1120
	s_mov_b32 s74, -1
	v_mov_b32_e32 v9, v236
	s_cmpk_gt_i32 s96, 0xaff
	s_nop 0
	v_readfirstlane_b32 s1, v9
	s_cbranch_scc1 .LBB0_1120
	v_lshlrev_b32_e32 v0, 4, v9
	s_waitcnt lgkmcnt(0)
	v_add_u32_e32 v1, 0x2000, v0
	v_ashrrev_i32_e32 v2, 31, v1
	v_lshrrev_b32_e32 v2, 22, v2
	v_add_u32_e32 v2, v1, v2
	v_ashrrev_i32_e32 v8, 10, v2
	v_mul_i32_i24_e32 v2, 0x400, v8
	v_sub_u32_e32 v1, v1, v2
	v_lshrrev_b32_e32 v2, 4, v1
	v_bitop3_b32 v1, v2, v1, 32 bitop3:0x6c
	v_ashrrev_i32_e32 v2, 31, v1
	v_lshrrev_b32_e32 v2, 26, v2
	v_add_u32_e32 v2, v1, v2
	v_lshlrev_b32_e32 v3, 3, v8
	v_ashrrev_i32_e32 v10, 6, v2
	v_and_b32_e32 v3, -16, v3
	v_add_u32_e32 v3, v10, v3
	v_and_b32_e32 v4, 3, v10
	s_mov_b32 s0, 0x1fffe0
	v_lshrrev_b32_e32 v5, 2, v3
	v_lshlrev_b32_e32 v6, 1, v3
	v_and_b32_e32 v2, 0xc0, v2
	v_and_or_b32 v4, v3, s0, v4
	v_and_b32_e32 v5, 4, v5
	v_and_b32_e32 v6, 24, v6
	v_sub_u32_e32 v1, v1, v2
	v_mov_b32_e32 v2, 1
	v_or3_b32 v4, v4, v5, v6
	v_lshlrev_b32_e32 v5, 5, v8
	v_ashrrev_i16_sdwa v1, v2, sext(v1) dst_sel:DWORD dst_unused:UNUSED_PAD src0_sel:DWORD src1_sel:BYTE_0
	v_and_b32_e32 v5, 32, v5
	v_bfe_i32 v11, v1, 0, 16
	v_add_lshl_u32 v1, v5, v11, 1
	v_lshl_add_u32 v144, v4, 11, v1
	v_lshl_add_u32 v146, v3, 11, v1
	v_bfe_i32 v1, v9, 27, 1
	v_lshrrev_b32_e32 v1, 22, v1
	v_add_u32_e32 v1, v0, v1
	v_and_b32_e32 v1, 0xfffffc00, v1
	v_sub_u32_e32 v0, v0, v1
	v_lshrrev_b32_e32 v1, 4, v0
	v_bitop3_b32 v1, v1, v0, 32 bitop3:0x6c
	v_ashrrev_i32_e32 v0, 31, v0
	v_lshrrev_b32_e32 v0, 26, v0
	v_add_u32_e32 v0, v1, v0
	v_ashrrev_i32_e32 v12, 6, v0
	v_ashrrev_i32_e32 v0, 31, v9
	v_lshrrev_b32_e32 v0, 26, v0
	v_add_u32_e32 v0, v9, v0
	s_add_u32 s2, s82, 0x16000000
	v_ashrrev_i32_e32 v13, 6, v0
	s_addc_u32 s3, s83, 0
	v_lshlrev_b32_e32 v0, 3, v13
	s_add_u32 s30, s82, 0x1300000
	v_and_b32_e32 v0, -16, v0
	s_addc_u32 s31, s83, 0
	v_add_u32_e32 v0, v12, v0
	v_and_b32_e32 v3, 3, v12
	s_ashr_i32 s34, s96, 31
	v_and_or_b32 v3, v0, s0, v3
	s_lshr_b32 s0, s34, 29
	s_add_i32 s0, s96, s0
	s_ashr_i32 s10, s1, 6
	s_ashr_i32 s6, s0, 3
	s_and_b32 s0, s0, -8
	s_ashr_i32 s12, s1, 8
	s_lshl_b32 s33, s10, 10
	s_sub_i32 s0, s96, s0
	s_cmp_lt_i32 s0, 0
	s_movk_i32 s35, 0x161
	s_cselect_b32 s7, s35, 0x160
	s_mul_i32 s0, s0, s7
	s_add_i32 s0, s0, s6
	s_mul_hi_i32 s6, s0, 0x2e8ba2e9
	s_lshr_b32 s7, s6, 31
	s_ashr_i32 s6, s6, 5
	s_add_i32 s6, s6, s7
	s_lshl_b32 s7, s6, 3
	s_mulk_i32 s6, 0xb0
	s_sub_i32 s6, s0, s6
	s_sext_i32_i16 s0, s6
	s_bfe_u32 s0, s0, 0x3001c
	s_add_i32 s8, s6, s0
	s_sext_i32_i16 s0, s8
	s_and_b32 s8, s8, 0xfff8
	v_lshrrev_b32_e32 v4, 2, v0
	v_lshlrev_b32_e32 v5, 1, v0
	s_sub_i32 s6, s6, s8
	v_and_b32_e32 v4, 4, v4
	v_and_b32_e32 v5, 24, v5
	s_sext_i32_i16 s6, s6
	v_or3_b32 v3, v3, v4, v5
	v_mul_i32_i24_e32 v5, 64, v12
	s_lshr_b32 s0, s0, 3
	s_add_i32 s22, s7, s6
	v_sub_u32_e32 v1, v1, v5
	s_ashr_i32 s23, s22, 31
	s_bfe_i64 s[8:9], s[0:1], 0x100000
	v_lshlrev_b32_e32 v4, 5, v13
	v_ashrrev_i16_sdwa v1, v2, sext(v1) dst_sel:DWORD dst_unused:UNUSED_PAD src0_sel:DWORD src1_sel:BYTE_0
	s_lshl_b64 s[6:7], s[22:23], 19
	s_lshl_b64 s[8:9], s[8:9], 19
	v_and_b32_e32 v4, 32, v4
	v_bfe_i32 v14, v1, 0, 16
	s_add_u32 s26, s30, s8
	v_add_lshl_u32 v1, v4, v14, 1
	s_addc_u32 s27, s31, s9
	s_add_i32 s23, s33, 0
	v_lshl_add_u32 v148, v3, 11, v1
	s_add_i32 m0, s23, 0x10000
	v_lshl_add_u32 v150, v0, 11, v1
	global_load_lds_dwordx4 v148, s[26:27]
	s_add_i32 m0, s23, 0x12000
	s_add_u32 s8, s26, 0x40000
	global_load_lds_dwordx4 v144, s[26:27]
	s_addc_u32 s9, s27, 0
	s_add_i32 m0, s23, 0x14000
	v_mov_b32_e32 v149, 0
	global_load_lds_dwordx4 v148, s[8:9]
	s_add_i32 m0, s23, 0x16000
	s_add_u32 s24, s2, s6
	s_addc_u32 s25, s3, s7
	s_add_i32 s36, s23, 0x2000
	global_load_lds_dwordx4 v144, s[8:9]
	s_mov_b32 m0, s23
	s_add_u32 s6, s24, 0x40000
	global_load_lds_dwordx4 v150, s[24:25]
	s_mov_b32 m0, s36
	s_addc_u32 s7, s25, 0
	s_add_i32 s37, s23, 0x4000
	global_load_lds_dwordx4 v146, s[24:25]
	s_mov_b32 m0, s37
	s_add_i32 s38, s23, 0x6000
	global_load_lds_dwordx4 v150, s[6:7]
	s_mov_b32 m0, s38
	v_mov_b32_e32 v145, v149
	global_load_lds_dwordx4 v146, s[6:7]
	v_mov_b32_e32 v151, v149
	v_mov_b32_e32 v147, v149
	s_cmp_eq_u32 s12, 1
	s_mov_b32 s39, 0
	v_lshl_add_u64 v[6:7], s[26:27], 0, v[148:149]
	v_lshl_add_u64 v[4:5], s[26:27], 0, v[144:145]
	v_lshl_add_u64 v[0:1], s[24:25], 0, v[150:151]
	s_cselect_b64 s[6:7], -1, 0
	s_cmp_lg_u32 s12, 1
	v_lshl_add_u64 v[2:3], s[24:25], 0, v[146:147]
	s_cbranch_scc1 .LBB0_1107
	s_barrier

.LBB0_1116:
	s_cmp_eq_u32 s22, s74
	s_cbranch_scc1 .Lrs_done
	s_mov_b32 s74, s22
	v_cmp_gt_u32_e32 vcc, 0x100, v236
	s_and_saveexec_b64 s[76:77], vcc
	s_cbranch_execz .Lrs_wait
	v_lshl_add_u32 v237, s22, 8, v236
	v_lshlrev_b32_e32 v237, 2, v237
	s_add_u32 s78, s82, 0x200000
	s_addc_u32 s79, s83, 0
	global_load_dword v238, v237, s[78:79]
	s_add_u32 s78, s78, 0x20000
	s_addc_u32 s79, s79, 0
	global_load_dword v239, v237, s[78:79]
	s_add_u32 s78, s78, 0x20000
	s_addc_u32 s79, s79, 0
	global_load_dword v240, v237, s[78:79]
	s_add_u32 s78, s78, 0x20000
	s_addc_u32 s79, s79, 0
	global_load_dword v241, v237, s[78:79]
	s_add_u32 s78, s78, 0x20000
	s_addc_u32 s79, s79, 0
	global_load_dword v242, v237, s[78:79]
	s_add_u32 s78, s78, 0x20000
	s_addc_u32 s79, s79, 0
	global_load_dword v243, v237, s[78:79]
	s_add_u32 s78, s78, 0x20000
	s_addc_u32 s79, s79, 0
	global_load_dword v244, v237, s[78:79]
	s_add_u32 s78, s78, 0x20000
	s_addc_u32 s79, s79, 0
	global_load_dword v245, v237, s[78:79]
	s_add_u32 s78, s78, 0x20000
	s_addc_u32 s79, s79, 0
	global_load_dword v246, v237, s[78:79]
	s_add_u32 s78, s78, 0x20000
	s_addc_u32 s79, s79, 0
	global_load_dword v247, v237, s[78:79]
	s_add_u32 s78, s78, 0x20000
	s_addc_u32 s79, s79, 0
	global_load_dword v248, v237, s[78:79]
	s_add_u32 s78, s78, 0x20000
	s_addc_u32 s79, s79, 0
	global_load_dword v249, v237, s[78:79]
	s_add_u32 s78, s78, 0x20000
	s_addc_u32 s79, s79, 0
	global_load_dword v250, v237, s[78:79]
	s_add_u32 s78, s78, 0x20000
	s_addc_u32 s79, s79, 0
	global_load_dword v251, v237, s[78:79]
	s_add_u32 s78, s78, 0x20000
	s_addc_u32 s79, s79, 0
	global_load_dword v252, v237, s[78:79]
	s_add_u32 s78, s78, 0x20000
	s_addc_u32 s79, s79, 0
	global_load_dword v253, v237, s[78:79]
	s_waitcnt vmcnt(8)
	v_add_f32_e32 v238, v238, v239
	v_add_f32_e32 v240, v240, v241
	v_add_f32_e32 v242, v242, v243
	v_add_f32_e32 v244, v244, v245
	s_waitcnt vmcnt(0)
	v_add_f32_e32 v246, v246, v247
	v_add_f32_e32 v248, v248, v249
	v_add_f32_e32 v250, v250, v251
	v_add_f32_e32 v252, v252, v253
	v_add_f32_e32 v238, v238, v240
	v_add_f32_e32 v242, v242, v244
	v_add_f32_e32 v246, v246, v248
	v_add_f32_e32 v250, v250, v252
	v_add_f32_e32 v238, v238, v242
	v_add_f32_e32 v246, v246, v250
	v_add_f32_e32 v238, v238, v246
	global_store_dword v237, v238, s[8:9]
	s_waitcnt vmcnt(0)
.Lrs_wait:
	s_or_b64 exec, exec, s[76:77]
	s_barrier
